# M2: rebalanced dilated-unit assignment (workgroups owning a uq-projection tile run 2 units, GEMM-free workgroups 6); attention queue robust to other grid sizes
# baseline (speedup 1.0000x reference)
; DI int ltid() { int t = threadIdx.x; asm volatile("" : "+v"(t)); return t; }
; #define QUEUE_BEGIN(n) for (;;) { __syncthreads(); if (tid == 0) *s_item = atomicAdd(WSP(int, WS_CTR) + ph + 50 * rep_, 1); __syncthreads(); const int item = *s_item; if (item >= (n)) break;
; __global__ void __launch_bounds__(512, 2) mega(Params p) {
;     ...
;             case OP_ATT_MLA: {
;     ...
;                 const int tid = ltid();
;                 QUEUE_BEGIN(512 + 256)
;                     if (item >= 256 && item < 512) {
;                         bf16_t* P = (bf16_t*)(R1 + R_P);
;                         const int qt = 15 - ((item - 256) >> 4), bl = (item >> 3) & 1, h = item & 7;
;                         AttnArgs a; a.Q = P + C_SBQ + h * 64; a.ldq = NINP; a.K = P + C_SBK + h * 64; a.ldk = NINP; a.K2 = nullptr; a.ldk2 = 0;
;                         a.V = P + C_SBV + h * 64; a.ldv = NINP; a.O = (bf16_t*)(R1 + R_OA) + h * 64; a.ldo = 512; a.lse = nullptr; a.ldl = 0;
;                         a.q0 = qt * 256; a.tstride = 1; a.toff = bl * SEQ; a.nk = 0; a.c2 = 0.125f * LOG2E; a.biasg = nullptr;
;                         attn_unit<2>(lds, a);
;                     } else if (item < 256) {
;                         const int qt = 15 - (item >> 4), bl = (item >> 3) & 1, h = item & 7;
;                         bf16_t* kvm = (bf16_t*)(R1 + R_KVM);
;                         AttnArgs a; a.Q = (bf16_t*)(R1 + R_QM) + h * 96; a.ldq = 768; a.K = kvm + h * 128; a.ldk = 1024; a.K2 = (bf16_t*)(R1 + R_P) + C_KR; a.ldk2 = NINP;
;                         a.V = kvm + h * 128 + 64; a.ldv = 1024; a.O = (bf16_t*)(R1 + R_OA) + (size_t)TC * 512 + h * 64; a.ldo = 512; a.lse = nullptr; a.ldl = 0;
;                         a.q0 = qt * 256; a.tstride = 1; a.toff = bl * SEQ; a.nk = 0; a.c2 = 0.10206207261596577f * LOG2E; a.biasg = nullptr;
;                         attn_unit<1>(lds, a);
;                     } else {
;                         const int t0 = (item - 512) * 32;
;                         bf16_t* oc = (bf16_t*)(R1 + R_OA) + (size_t)2 * TC * 512;
;                         const bf16_t* og = (const bf16_t*)(R1 + R_OG);
;                         const float* lse = (const float*)(R1 + R_LSE);
.LBB0_109:
	s_andn2_b64 vcc, exec, s[6:7]
	s_cbranch_vccnz .LBB0_223
	s_load_dwordx2 s[4:5], s[70:71], 0xe8
	v_readlane_b32 s0, v254, 6
	v_readlane_b32 s1, v254, 7
	s_lshl_b64 s[0:1], s[0:1], 2
	v_mov_b32_e32 v2, v202
	s_waitcnt lgkmcnt(0)
	s_add_u32 s0, s4, s0
	s_addc_u32 s1, s5, s1
	v_writelane_b32 v255, s0, 11
	s_nop 0
	v_lshrrev_b32_e32 v0, 1, v2
	v_writelane_b32 v255, s1, 12
	s_add_u32 s0, s4, 0xcb4a200
	s_addc_u32 s1, s5, 0
	v_writelane_b32 v255, s0, 13
	v_and_b32_e32 v0, 28, v0
	v_cmp_eq_u32_e64 s[12:13], 0, v2
	v_writelane_b32 v255, s1, 14
	s_add_u32 s0, s4, 0x1a349200
	v_writelane_b32 v255, s0, 15
	s_addc_u32 s0, s5, 0
	v_writelane_b32 v255, s0, 16
	s_add_u32 s0, s4, 0xcb49600
	v_writelane_b32 v255, s0, 17
	s_addc_u32 s0, s5, 0
	v_writelane_b32 v255, s0, 18
	s_add_u32 s0, s4, 0xcb49a00
	s_addc_u32 s1, s5, 0
	v_writelane_b32 v255, s0, 19
	v_ashrrev_i32_e32 v196, 6, v2
	v_add_u32_e32 v197, 0xffffc000, v196
	v_writelane_b32 v255, s1, 20
	s_nop 0
	v_readlane_b32 s0, v255, 9
	v_readlane_b32 s1, v255, 10
	s_nop 1
	v_lshl_add_u64 v[136:137], s[0:1], 0, v[0:1]
	v_readlane_b32 s0, v255, 7
	v_lshlrev_b32_e32 v0, 4, v2
	v_readlane_b32 s1, v255, 8
	v_writelane_b32 v255, s12, 21
	v_and_b32_e32 v0, 0x3f0, v0
	v_lshl_add_u64 v[138:139], s[0:1], 0, v[0:1]
	v_writelane_b32 v255, s13, 22
	v_lshl_add_u64 v[2:3], s[4:5], 0, v[0:1]
	s_mov_b64 s[0:1], 0x1ab49200
	v_writelane_b32 v255, s70, 23
	v_lshl_add_u64 v[140:141], v[2:3], 0, s[0:1]
	s_nop 0
	v_writelane_b32 v255, s71, 24
	v_readlane_b32 s99, v255, 1
	s_cmp_eq_u32 s99, 0x100
	s_cselect_b32 s99, 1, 0
	s_cselect_b32 s101, 0x100, 0
	s_branch .LBB0_114

.LBB0_118:
	s_or_b64 exec, exec, s[6:7]
	s_mov_b32 s0, 0x20000
	s_addk_i32 s0, 0x100
	v_mov_b32_e32 v0, s0
	s_waitcnt lgkmcnt(0)
	s_barrier
	ds_read_b32 v0, v0
	s_movk_i32 s0, 0x31f
	s_sub_i32 s0, s0, s101
	s_mov_b64 s[6:7], -1
	s_waitcnt lgkmcnt(0)
	v_cmp_lt_i32_e32 vcc, s0, v0
	v_readfirstlane_b32 s18, v0
	s_cbranch_vccnz .LBB0_113
	s_add_i32 s18, s18, s101

; DI unsigned pk2(float lo, float hi) { f32x2_t v = {lo, hi}; bf16x2_t b = __builtin_convertvector(v, bf16x2_t); return __builtin_bit_cast(unsigned, b); }
; DI float lg2(float x) { return __builtin_amdgcn_logf(x); }
; DI int ltid() { int t = threadIdx.x; asm volatile("" : "+v"(t)); return t; }
; DI void attn_dil_unit(LAS unsigned char* lds, const AttnArgs a) {
;     ...
;     const float inv = 1.0f / lt;
;     if (hh == 0) a.lse[qtok * a.ldl] = mx + lg2(lt);
; #pragma unroll
;     for (int d = 0; d < 2; ++d)
; #pragma unroll
;         for (int g4 = 0; g4 < 4; ++g4) {
;             u32x2 w; w.x = pk2(o[d][4 * g4] * inv, o[d][4 * g4 + 1] * inv); w.y = pk2(o[d][4 * g4 + 2] * inv, o[d][4 * g4 + 3] * inv);
;             *(u32x2*)(a.O + qtok * a.ldo + d * 32 + 8 * g4 + 4 * hh) = w;
;         }
; __global__ void __launch_bounds__(512, 2) mega(Params p) {
;     ...
;                 const int tid = ltid();
;                 bf16_t* P = (bf16_t*)(R1 + R_P);
;                 for (int item = bid; item < 768; item += G) {
;                     {
;                         const int j = item, g = j >> 8, bl = (j >> 7) & 1, h = (j >> 4) & 7, sub = j & 15;
;                         const int r = (g == 0) ? 1 : (g == 1 ? 4 : 16), cls = sub % r, qt = sub / r;
;                         const bf16_t* base = P + C_DIL + g * 1536 + h * 64;
;                         AttnArgs a; a.Q = base; a.ldq = NINP; a.K = base + 512; a.ldk = NINP; a.K2 = nullptr; a.ldk2 = 0;
;                         a.V = base + 1024; a.ldv = NINP; a.O = (bf16_t*)(R1 + R_OG) + (size_t)g * TC * 512 + h * 64; a.ldo = 512;
;                         a.lse = (float*)(R1 + R_LSE) + (size_t)g * TC * 8 + h; a.ldl = 8;
;                         a.q0 = qt * 256; a.tstride = r; a.toff = bl * SEQ + cls; a.nk = 0; a.c2 = 0.125f * LOG2E; a.biasg = WSP(float, WS_BIAS) + (g * 8 + h) * 132;
;                         attn_dil_unit(lds, a);
;                     }
;                 }
.LBB0_224:
	s_andn2_b64 vcc, exec, s[6:7]
	s_cbranch_vccnz .LBB0_234
	v_readlane_b32 s0, v253, 8
	v_readlane_b32 s1, v253, 9
	v_mov_b32_e32 v0, v202
	s_andn2_b64 vcc, exec, s[0:1]
	s_cbranch_vccnz .LBB0_234
	v_readlane_b32 s0, v254, 61
	v_readlane_b32 s1, v254, 62
	s_add_u32 s16, s0, 0xcb4a400
	s_addc_u32 s17, s1, 0
	v_readlane_b32 s0, v255, 1
	s_lshl_b32 s18, s0, 5
	v_readlane_b32 s19, v253, 51
	s_mov_b32 s20, s76
	s_mov_b32 s99, 0
	s_cmp_eq_u32 s0, 0x100
	s_cselect_b32 s101, 1, 0
	v_readlane_b32 s1, v255, 2
	s_branch .LBB0_228
.LBB0_227:
	s_or_b64 exec, exec, s[6:7]
	s_lshl_b32 s4, s21, 6
	s_lshl_b64 s[0:1], s[14:15], 23
	v_readlane_b32 s6, v255, 7
	v_readlane_b32 s7, v255, 8
	s_add_u32 s5, s6, s0
	s_addc_u32 s6, s7, s1
	v_div_scale_f32 v34, s[0:1], v0, v0, 1.0
	v_rcp_f32_e32 v35, v34
	s_lshl_b32 s0, s4, 1
	s_add_u32 s0, s5, s0
	s_addc_u32 s1, s6, 0
	v_fma_f32 v36, -v34, v35, 1.0
	v_fmac_f32_e32 v35, v36, v35
	v_div_scale_f32 v36, vcc, 1.0, v0, 1.0
	v_mul_f32_e32 v37, v36, v35
	v_fma_f32 v38, -v34, v37, v36
	v_fmac_f32_e32 v37, v38, v35
	v_fma_f32 v34, -v34, v37, v36
	v_div_fmas_f32 v34, v34, v35, v37
	v_div_fixup_f32 v34, v34, v0, 1.0
	v_lshlrev_b64 v[36:37], 10, v[94:95]
	v_lshl_add_u64 v[36:37], s[0:1], 0, v[36:37]
	v_lshlrev_b32_e32 v0, 1, v92
	v_pk_mul_f32 v[18:19], v[18:19], v[34:35] op_sel_hi:[1,0]
	v_pk_mul_f32 v[20:21], v[20:21], v[34:35] op_sel_hi:[1,0]
	v_pk_mul_f32 v[2:3], v[2:3], v[34:35] op_sel_hi:[1,0]
	v_pk_mul_f32 v[4:5], v[4:5], v[34:35] op_sel_hi:[1,0]
	v_lshl_add_u64 v[36:37], v[36:37], 0, v[0:1]
	v_cvt_pk_bf16_f32 v18, v18, v19
	v_cvt_pk_bf16_f32 v19, v20, v21
	v_cvt_pk_bf16_f32 v2, v2, v3
	v_cvt_pk_bf16_f32 v3, v4, v5
	global_store_dwordx2 v[36:37], v[18:19], off
	v_pk_mul_f32 v[18:19], v[22:23], v[34:35] op_sel_hi:[1,0]
	v_pk_mul_f32 v[20:21], v[24:25], v[34:35] op_sel_hi:[1,0]
	global_store_dwordx2 v[36:37], v[2:3], off offset:64
	v_pk_mul_f32 v[2:3], v[6:7], v[34:35] op_sel_hi:[1,0]
	v_pk_mul_f32 v[4:5], v[8:9], v[34:35] op_sel_hi:[1,0]
	v_cvt_pk_bf16_f32 v18, v18, v19
	v_cvt_pk_bf16_f32 v19, v20, v21
	v_cvt_pk_bf16_f32 v2, v2, v3
	v_cvt_pk_bf16_f32 v3, v4, v5
	global_store_dwordx2 v[36:37], v[18:19], off offset:16
	v_pk_mul_f32 v[18:19], v[26:27], v[34:35] op_sel_hi:[1,0]
	v_pk_mul_f32 v[20:21], v[28:29], v[34:35] op_sel_hi:[1,0]
	global_store_dwordx2 v[36:37], v[2:3], off offset:80
	v_pk_mul_f32 v[2:3], v[10:11], v[34:35] op_sel_hi:[1,0]
	v_pk_mul_f32 v[4:5], v[12:13], v[34:35] op_sel_hi:[1,0]
	v_cvt_pk_bf16_f32 v18, v18, v19
	v_cvt_pk_bf16_f32 v19, v20, v21
	v_cvt_pk_bf16_f32 v2, v2, v3
	v_cvt_pk_bf16_f32 v3, v4, v5
	v_readlane_b32 s0, v255, 1
	global_store_dwordx2 v[36:37], v[18:19], off offset:32
	v_pk_mul_f32 v[18:19], v[30:31], v[34:35] op_sel_hi:[1,0]
	v_pk_mul_f32 v[20:21], v[32:33], v[34:35] op_sel_hi:[1,0]
	global_store_dwordx2 v[36:37], v[2:3], off offset:96
	v_pk_mul_f32 v[2:3], v[14:15], v[34:35] op_sel_hi:[1,0]
	v_pk_mul_f32 v[4:5], v[16:17], v[34:35] op_sel_hi:[1,0]
	v_cvt_pk_bf16_f32 v18, v18, v19
	v_cvt_pk_bf16_f32 v19, v20, v21
	v_cvt_pk_bf16_f32 v2, v2, v3
	v_cvt_pk_bf16_f32 v3, v4, v5
	global_store_dwordx2 v[36:37], v[18:19], off offset:48
	v_readlane_b32 s1, v255, 2
	global_store_dwordx2 v[36:37], v[2:3], off offset:112
	s_cmp_lg_u32 s101, 0
	s_cbranch_scc1 .Ldq_static
	s_add_i32 s20, s20, s0
	s_add_i32 s19, s19, s18
	s_cmpk_gt_i32 s20, 0x2ff
	s_cbranch_scc1 .LBB0_234
	s_branch .LBB0_228
.Ldq_static:
	s_add_i32 s99, s99, 1
	s_lshl_b32 s20, s99, 8
	s_add_i32 s20, s20, s76
	s_cmp_lt_u32 s99, 2
	s_cbranch_scc1 .Ldq_go
	s_cmp_eq_u32 s99, 2
	s_cbranch_scc0 .Ldq_extra
	s_cmp_lt_u32 s76, 96
	s_cbranch_scc1 .LBB0_234
	s_branch .Ldq_go
.Ldq_extra:
	s_cmp_lt_u32 s76, 0xe0
	s_cbranch_scc1 .LBB0_234
	s_cmp_gt_u32 s99, 5
	s_cbranch_scc1 .LBB0_234
	s_sub_i32 s20, s76, 0xe0
	s_mul_i32 s20, s20, 3
	s_add_i32 s20, s20, s99
	s_addk_i32 s20, 0x1fd
.Ldq_go:
	s_lshl_b32 s19, s20, 5
